# static s_setprio 1 at kernel entry for workgroups in the lower half of the grid
# speedup vs baseline: 1.0083x; 1.0011x over previous
; #define LAS __attribute__((address_space(3)))
; DI void rwkv_carry(const Params& p, float* rwst) {
;     ...
;   const int wsel = ((int)blockIdx.x < (int)(gridDim.x >> 1)) ? wave : wave - 2;
; __global__ void __launch_bounds__(256, 2) fwd_megakernel(KArgs k) {
;   __shared__ __attribute__((aligned(16))) char smem_raw[SMEM_BYTES];
;   __shared__ uint4 xb_words;
;   cg::grid_group grid = cg::this_grid();
;   const Params p = make_params(k);
;   if (__builtin_amdgcn_workitem_id_x() == 0) xb_words = make_uint4(0u, 0u, 0u, 0u);
;   __syncthreads();
;   const XcdBarrier xb = xcd_barrier_post((unsigned*)(k.ws + O_bar), (volatile LAS unsigned*)&xb_words);
_Z14fwd_megakernel5KArgs:
	s_mov_b32 s8, s2
	s_load_dwordx16 s[48:63], s[0:1], 0x140
	s_load_dword s2, s[0:1], 0x188
	v_and_b32_e32 v210, 0x3ff, v0
	v_cmp_eq_u32_e64 s[4:5], 0, v210
	s_waitcnt lgkmcnt(0)
	v_writelane_b32 v252, s2, 0
	s_load_dwordx2 s[2:3], s[0:1], 0x180
	s_waitcnt lgkmcnt(0)
	v_writelane_b32 v252, s2, 1
	s_nop 1
	v_writelane_b32 v252, s3, 2
	s_lshr_b32 s3, s2, 1
	s_cmp_ge_u32 s8, s3
	s_cbranch_scc1 .Lprio_skip
	s_setprio 1
